# attention: relative-position bias + window mask made branch-free (v_cndmask) with LDS reads batched 16 at a time (was 64 exec-masked branches with one LDS round trip each); V ring prologue moved ahead
# baseline (speedup 1.0000x reference)
; template <bool LOCAL>
; __device__ __forceinline__ void attn_unit(const bf16_t* Q, const bf16_t* KT, const bf16_t* VT, bf16_t* O, LAS unsigned char* lds, int b, int h, int r, int w, int tq, int lane) {
;     ...
;     float mx = -INFINITY;
; #pragma unroll
;     for (int i = 0; i < 2 * NP; ++i) mx = fmaxf(mx, fmaxf(fmaxf(s[i][0], s[i][1]), fmaxf(s[i][2], s[i][3])));
;     mx = fmaxf(mx, __shfl_xor(mx, 16)); mx = fmaxf(mx, __shfl_xor(mx, 32));
.LBB9_673:
	s_or_b64 exec, exec, s[34:35]
	v_max_f32_e32 v66, v126, v126
	v_max_f32_e32 v67, v134, v134
	v_max_f32_e32 v66, v67, v66
	v_max_f32_e32 v67, v123, v123
	v_max_f32_e32 v68, v129, v129
	v_max_f32_e32 v67, v68, v67
	v_max3_f32 v66, v133, v132, v66
	v_max3_f32 v67, v128, v127, v67
	v_max3_f32 v66, v66, s16, v67
	v_max_f32_e32 v67, v118, v118
	v_max_f32_e32 v68, v125, v125
	v_max_f32_e32 v67, v68, v67
	v_max_f32_e32 v68, v115, v115
	v_max_f32_e32 v69, v121, v121
	v_max_f32_e32 v68, v69, v68
	v_max3_f32 v67, v124, v122, v67
	v_max3_f32 v68, v120, v119, v68
	v_max3_f32 v66, v66, v67, v68
	v_max_f32_e32 v67, v110, v110
	v_max_f32_e32 v68, v117, v117
	v_max_f32_e32 v67, v68, v67
	v_max_f32_e32 v68, v113, v113
	v_max_f32_e32 v69, v135, v135
	v_max_f32_e32 v68, v69, v68
	v_max3_f32 v67, v116, v114, v67
	v_max3_f32 v68, v112, v111, v68
	v_max3_f32 v66, v66, v67, v68
	v_max_f32_e32 v67, v102, v102
	v_max_f32_e32 v68, v109, v109
	v_max_f32_e32 v67, v68, v67
	v_max_f32_e32 v68, v99, v99
	v_max_f32_e32 v69, v105, v105
	v_max_f32_e32 v68, v69, v68
	v_max3_f32 v67, v108, v107, v67
	v_max3_f32 v68, v104, v103, v68
	v_max3_f32 v66, v66, v67, v68
	v_max_f32_e32 v67, v94, v94
	v_max_f32_e32 v68, v101, v101
	v_max_f32_e32 v67, v68, v67
	v_max_f32_e32 v68, v91, v91
	v_max_f32_e32 v69, v97, v97
	v_max_f32_e32 v68, v69, v68
	v_max3_f32 v67, v100, v98, v67
	v_max3_f32 v68, v96, v95, v68
	v_max3_f32 v66, v66, v67, v68
	v_max_f32_e32 v67, v86, v86
	v_max_f32_e32 v68, v93, v93
	v_max_f32_e32 v67, v68, v67
	v_max_f32_e32 v68, v89, v89
	v_max_f32_e32 v69, v138, v138
	v_max_f32_e32 v68, v69, v68
	v_max3_f32 v67, v92, v90, v67
	v_max3_f32 v68, v88, v87, v68
	v_max3_f32 v66, v66, v67, v68
	v_max_f32_e32 v67, v139, v139
	v_max_f32_e32 v68, v141, v141
	v_max_f32_e32 v67, v68, v67
	v_max_f32_e32 v68, v197, v197
	v_max_f32_e32 v69, v199, v199
	v_max_f32_e32 v68, v69, v68
	v_max3_f32 v67, v137, v136, v67
	v_max3_f32 v68, v195, v140, v68
	v_max3_f32 v66, v66, v67, v68
	v_max_f32_e32 v67, v200, v200
	v_max_f32_e32 v68, v202, v202
	v_max_f32_e32 v67, v68, v67
	v_max_f32_e32 v68, v204, v204
	v_max_f32_e32 v69, v205, v205
	v_max_f32_e32 v68, v69, v68
	v_max3_f32 v67, v198, v196, v67
	v_max3_f32 v68, v203, v201, v68
	v_max3_f32 v66, v66, v67, v68
	v_max_f32_e32 v67, v5, v5
	v_max_f32_e32 v68, v4, v4
	v_max_f32_e32 v67, v68, v67
	v_max_f32_e32 v68, v13, v13
	v_max_f32_e32 v69, v12, v12
	v_max_f32_e32 v68, v69, v68
	v_max3_f32 v67, v2, v3, v67
	v_max3_f32 v68, v10, v11, v68
	v_max3_f32 v66, v66, v67, v68
	v_max_f32_e32 v67, v9, v9
	v_max_f32_e32 v68, v8, v8
	v_max_f32_e32 v67, v68, v67
	v_max_f32_e32 v68, v21, v21
	v_max_f32_e32 v69, v20, v20
	v_max_f32_e32 v68, v69, v68
	v_max3_f32 v67, v6, v7, v67
	v_max3_f32 v68, v18, v19, v68
	v_max3_f32 v66, v66, v67, v68
	v_max_f32_e32 v67, v17, v17
	v_max_f32_e32 v68, v16, v16
	v_max_f32_e32 v67, v68, v67
	v_max_f32_e32 v68, v29, v29
	v_max_f32_e32 v69, v28, v28
	v_max_f32_e32 v68, v69, v68
	v_max3_f32 v67, v14, v15, v67
	v_max3_f32 v68, v26, v27, v68
	v_max3_f32 v66, v66, v67, v68
	v_max_f32_e32 v67, v25, v25
	v_max_f32_e32 v68, v24, v24
	v_max_f32_e32 v67, v68, v67
	v_max_f32_e32 v68, v37, v37
	v_max_f32_e32 v69, v36, v36
	v_max_f32_e32 v68, v69, v68
	v_max3_f32 v67, v22, v23, v67
	v_max3_f32 v68, v34, v35, v68
	v_max3_f32 v66, v66, v67, v68
	v_max_f32_e32 v67, v33, v33
	v_max_f32_e32 v68, v32, v32
	v_max_f32_e32 v67, v68, v67
	v_max_f32_e32 v68, v45, v45
	v_max_f32_e32 v69, v44, v44
	v_max_f32_e32 v68, v69, v68
	v_max3_f32 v67, v30, v31, v67
	v_max3_f32 v68, v42, v43, v68
	v_max3_f32 v66, v66, v67, v68
	v_max_f32_e32 v67, v41, v41
	v_max_f32_e32 v68, v40, v40
	v_max_f32_e32 v67, v68, v67
	v_max_f32_e32 v68, v53, v53
	v_max_f32_e32 v69, v52, v52
	v_max_f32_e32 v68, v69, v68
	v_max3_f32 v67, v38, v39, v67
	v_max3_f32 v68, v50, v51, v68
	v_max3_f32 v66, v66, v67, v68
	v_max_f32_e32 v67, v49, v49
	v_max_f32_e32 v68, v48, v48
	v_max_f32_e32 v67, v68, v67
	v_max_f32_e32 v68, v61, v61
	v_max_f32_e32 v69, v60, v60
	v_max_f32_e32 v68, v69, v68
	v_max3_f32 v67, v46, v47, v67
	v_max3_f32 v68, v58, v59, v68
	v_max3_f32 v66, v66, v67, v68
	v_max_f32_e32 v67, v57, v57
	v_max_f32_e32 v68, v56, v56
	v_max_f32_e32 v67, v68, v67
	v_max_f32_e32 v68, v65, v65
	v_max_f32_e32 v69, v64, v64
	v_max_f32_e32 v68, v69, v68
	v_max3_f32 v67, v54, v55, v67
	v_max3_f32 v68, v62, v63, v68
	v_max3_f32 v66, v66, v67, v68
	ds_bpermute_b32 v67, v181, v66
	v_lshlrev_b64 v[130:131], 11, v[162:163]
	s_waitcnt lgkmcnt(0)
	v_max_f32_e32 v67, v67, v67
	v_max_f32_e32 v66, v66, v67
	ds_bpermute_b32 v67, v182, v66
	s_waitcnt lgkmcnt(0)
; __device__ __forceinline__ unsigned cvt_pk_bf16(float lo, float hi) { unsigned r; asm volatile("v_cvt_pk_bf16_f32 %0, %1, %2" : "=v"(r) : "v"(lo), "v"(hi)); return r; }
; __device__ __forceinline__ float fast_exp2(float x) { return __builtin_amdgcn_exp2f(x); }
; template <bool LOCAL>
; __device__ __forceinline__ void attn_unit(const bf16_t* Q, const bf16_t* KT, const bf16_t* VT, bf16_t* O, LAS unsigned char* lds, int b, int h, int r, int w, int tq, int lane) {
;     ...
;     float sum = 0.f; const float mxl = mx * 1.4426950408889634f;
;     bf16x8 pb[NP];
; #pragma unroll
;     for (int p = 0; p < NP; ++p) { float e[8];
; #pragma unroll
;         for (int f = 0; f < 2; ++f)
; #pragma unroll
;             for (int j = 0; j < 4; ++j) { e[4 * f + j] = fast_exp2(fmaf(s[2 * p + f][j], 1.4426950408889634f, -mxl)); sum += e[4 * f + j]; }
;         u32x4 pw; pw.x = cvt_pk_bf16(e[0], e[1]); pw.y = cvt_pk_bf16(e[2], e[3]); pw.z = cvt_pk_bf16(e[4], e[5]); pw.w = cvt_pk_bf16(e[6], e[7]);
;         pb[p] = __builtin_bit_cast(bf16x8, pw); }
	v_max_f32_e32 v67, v67, v67
	v_max_f32_e32 v66, v66, v67
	v_mul_f32_e32 v106, 0xbfb8aa3b, v66
	v_fmamk_f32 v66, v133, 0x3fb8aa3b, v106
	v_exp_f32_e32 v66, v66
	v_fmamk_f32 v68, v132, 0x3fb8aa3b, v106
	v_exp_f32_e32 v68, v68
	v_fmamk_f32 v69, v134, 0x3fb8aa3b, v106
	v_exp_f32_e32 v69, v69
	v_fmamk_f32 v70, v126, 0x3fb8aa3b, v106
	v_exp_f32_e32 v70, v70
	v_fmamk_f32 v71, v128, 0x3fb8aa3b, v106
	v_add_f32_e32 v67, 0, v66
	v_exp_f32_e32 v71, v71
	v_fmamk_f32 v72, v127, 0x3fb8aa3b, v106
	v_add_f32_e32 v67, v68, v67
	v_exp_f32_e32 v72, v72
	v_fmamk_f32 v73, v129, 0x3fb8aa3b, v106
	v_add_f32_e32 v67, v69, v67
	v_exp_f32_e32 v73, v73
	v_fmamk_f32 v74, v123, 0x3fb8aa3b, v106
	v_add_f32_e32 v67, v70, v67
	v_exp_f32_e32 v74, v74
	v_add_f32_e32 v67, v71, v67
	v_add_f32_e32 v67, v72, v67
	v_add_f32_e32 v67, v73, v67
	v_add_f32_e32 v75, v74, v67
	v_cvt_pk_bf16_f32 v66, v66, v68
	v_cvt_pk_bf16_f32 v67, v69, v70
	v_fmamk_f32 v70, v124, 0x3fb8aa3b, v106
	v_exp_f32_e32 v70, v70
	v_cvt_pk_bf16_f32 v68, v71, v72
	v_fmamk_f32 v72, v122, 0x3fb8aa3b, v106
	v_cvt_pk_bf16_f32 v69, v73, v74
	v_exp_f32_e32 v72, v72
	v_fmamk_f32 v73, v125, 0x3fb8aa3b, v106
	v_exp_f32_e32 v73, v73
	v_fmamk_f32 v74, v118, 0x3fb8aa3b, v106
	v_add_f32_e32 v71, v70, v75
	v_exp_f32_e32 v74, v74
	v_fmamk_f32 v75, v120, 0x3fb8aa3b, v106
	v_exp_f32_e32 v75, v75
	v_fmamk_f32 v76, v119, 0x3fb8aa3b, v106
	v_add_f32_e32 v71, v72, v71
	v_exp_f32_e32 v76, v76
	v_fmamk_f32 v77, v121, 0x3fb8aa3b, v106
	v_add_f32_e32 v71, v73, v71
	v_exp_f32_e32 v77, v77
	v_fmamk_f32 v78, v115, 0x3fb8aa3b, v106
	v_add_f32_e32 v71, v74, v71
	v_exp_f32_e32 v78, v78
	v_add_f32_e32 v71, v75, v71
	v_add_f32_e32 v71, v76, v71
	v_add_f32_e32 v71, v77, v71
	v_add_f32_e32 v79, v78, v71
	v_cvt_pk_bf16_f32 v70, v70, v72
	v_cvt_pk_bf16_f32 v71, v73, v74
	v_fmamk_f32 v74, v116, 0x3fb8aa3b, v106
	v_exp_f32_e32 v74, v74
	v_cvt_pk_bf16_f32 v72, v75, v76
	v_fmamk_f32 v76, v114, 0x3fb8aa3b, v106
	v_cvt_pk_bf16_f32 v73, v77, v78
	v_exp_f32_e32 v76, v76
	v_fmamk_f32 v77, v117, 0x3fb8aa3b, v106
	v_exp_f32_e32 v77, v77
	v_fmamk_f32 v78, v110, 0x3fb8aa3b, v106
	v_add_f32_e32 v75, v74, v79
	v_exp_f32_e32 v78, v78
	v_fmamk_f32 v79, v112, 0x3fb8aa3b, v106
	v_exp_f32_e32 v79, v79
	v_fmamk_f32 v80, v111, 0x3fb8aa3b, v106
	v_add_f32_e32 v75, v76, v75
	v_exp_f32_e32 v80, v80
	v_fmamk_f32 v81, v135, 0x3fb8aa3b, v106
	v_add_f32_e32 v75, v77, v75
	v_exp_f32_e32 v81, v81
	v_fmamk_f32 v82, v113, 0x3fb8aa3b, v106
	v_add_f32_e32 v75, v78, v75
	v_exp_f32_e32 v82, v82
	v_add_f32_e32 v75, v79, v75
	v_add_f32_e32 v75, v80, v75
	v_add_f32_e32 v75, v81, v75
	v_add_f32_e32 v83, v82, v75
	v_cvt_pk_bf16_f32 v74, v74, v76
	v_cvt_pk_bf16_f32 v75, v77, v78
	v_fmamk_f32 v78, v108, 0x3fb8aa3b, v106
	v_exp_f32_e32 v78, v78
	v_cvt_pk_bf16_f32 v76, v79, v80
	v_fmamk_f32 v80, v107, 0x3fb8aa3b, v106
	v_cvt_pk_bf16_f32 v77, v81, v82
	v_exp_f32_e32 v80, v80
	v_fmamk_f32 v81, v109, 0x3fb8aa3b, v106
	v_exp_f32_e32 v81, v81
	v_fmamk_f32 v82, v102, 0x3fb8aa3b, v106
	v_add_f32_e32 v79, v78, v83
	v_exp_f32_e32 v82, v82
	v_fmamk_f32 v83, v104, 0x3fb8aa3b, v106
	v_exp_f32_e32 v83, v83
	v_fmamk_f32 v84, v103, 0x3fb8aa3b, v106
	v_add_f32_e32 v79, v80, v79
	v_exp_f32_e32 v84, v84
	v_fmamk_f32 v85, v105, 0x3fb8aa3b, v106
	v_add_f32_e32 v79, v81, v79
	v_exp_f32_e32 v85, v85
	v_fmamk_f32 v99, v99, 0x3fb8aa3b, v106
	v_add_f32_e32 v79, v82, v79
	v_exp_f32_e32 v99, v99
	v_add_f32_e32 v79, v83, v79
	v_add_f32_e32 v79, v84, v79
	v_add_f32_e32 v79, v85, v79
	v_add_f32_e32 v102, v99, v79
	v_cvt_pk_bf16_f32 v78, v78, v80
	v_cvt_pk_bf16_f32 v79, v81, v82
	v_fmamk_f32 v82, v100, 0x3fb8aa3b, v106
	v_cvt_pk_bf16_f32 v80, v83, v84
	v_exp_f32_e32 v82, v82
	v_fmamk_f32 v84, v98, 0x3fb8aa3b, v106
	v_cvt_pk_bf16_f32 v81, v85, v99
	v_exp_f32_e32 v84, v84
	v_fmamk_f32 v85, v101, 0x3fb8aa3b, v106
	v_exp_f32_e32 v85, v85
	v_fmamk_f32 v94, v94, 0x3fb8aa3b, v106
	v_exp_f32_e32 v94, v94
	v_fmamk_f32 v96, v96, 0x3fb8aa3b, v106
	v_add_f32_e32 v83, v82, v102
	v_exp_f32_e32 v96, v96
	v_fmamk_f32 v95, v95, 0x3fb8aa3b, v106
	v_add_f32_e32 v83, v84, v83
	v_exp_f32_e32 v95, v95
	v_fmamk_f32 v97, v97, 0x3fb8aa3b, v106
	v_add_f32_e32 v83, v85, v83
	v_exp_f32_e32 v97, v97
	v_fmamk_f32 v91, v91, 0x3fb8aa3b, v106
	v_add_f32_e32 v83, v94, v83
	v_exp_f32_e32 v91, v91
	v_add_f32_e32 v83, v96, v83
	v_add_f32_e32 v83, v95, v83
	v_add_f32_e32 v83, v97, v83
	v_add_f32_e32 v98, v91, v83
	v_cvt_pk_bf16_f32 v82, v82, v84
	v_cvt_pk_bf16_f32 v83, v85, v94
	v_cvt_pk_bf16_f32 v84, v96, v95
	v_cvt_pk_bf16_f32 v85, v97, v91
	v_fmamk_f32 v91, v92, 0x3fb8aa3b, v106
	v_exp_f32_e32 v91, v91
	v_fmamk_f32 v90, v90, 0x3fb8aa3b, v106
	v_exp_f32_e32 v90, v90
	v_fmamk_f32 v93, v93, 0x3fb8aa3b, v106
	v_exp_f32_e32 v93, v93
	v_fmamk_f32 v86, v86, 0x3fb8aa3b, v106
	v_exp_f32_e32 v94, v86
	v_add_f32_e32 v92, v91, v98
	v_add_f32_e32 v92, v90, v92
	v_fmamk_f32 v88, v88, 0x3fb8aa3b, v106
	v_add_f32_e32 v92, v93, v92
	v_exp_f32_e32 v88, v88
	v_fmamk_f32 v87, v87, 0x3fb8aa3b, v106
	v_add_f32_e32 v86, v94, v92
	v_exp_f32_e32 v92, v87
	v_fmamk_f32 v87, v138, 0x3fb8aa3b, v106
	v_exp_f32_e32 v95, v87
	v_fmamk_f32 v87, v89, 0x3fb8aa3b, v106
	v_exp_f32_e32 v89, v87
	v_add_f32_e32 v86, v88, v86
	v_add_f32_e32 v86, v92, v86
	v_add_f32_e32 v86, v95, v86
	v_add_f32_e32 v96, v89, v86
	v_cvt_pk_bf16_f32 v86, v91, v90
	v_fmamk_f32 v90, v137, 0x3fb8aa3b, v106
	v_cvt_pk_bf16_f32 v87, v93, v94
	v_cvt_pk_bf16_f32 v88, v88, v92
	v_exp_f32_e32 v90, v90
	v_fmamk_f32 v92, v136, 0x3fb8aa3b, v106
	v_exp_f32_e32 v92, v92
	v_fmamk_f32 v93, v141, 0x3fb8aa3b, v106
	v_exp_f32_e32 v93, v93
	v_fmamk_f32 v94, v139, 0x3fb8aa3b, v106
	v_cvt_pk_bf16_f32 v89, v95, v89
	v_exp_f32_e32 v95, v94
; __device__ __forceinline__ unsigned cvt_pk_bf16(float lo, float hi) { unsigned r; asm volatile("v_cvt_pk_bf16_f32 %0, %1, %2" : "=v"(r) : "v"(lo), "v"(hi)); return r; }
; __device__ __forceinline__ float fast_exp2(float x) { return __builtin_amdgcn_exp2f(x); }
; template <bool LOCAL>
; __device__ __forceinline__ void attn_unit(const bf16_t* Q, const bf16_t* KT, const bf16_t* VT, bf16_t* O, LAS unsigned char* lds, int b, int h, int r, int w, int tq, int lane) {
;     ...
;     float sum = 0.f; const float mxl = mx * 1.4426950408889634f;
;     bf16x8 pb[NP];
; #pragma unroll
;     for (int p = 0; p < NP; ++p) { float e[8];
; #pragma unroll
;         for (int f = 0; f < 2; ++f)
; #pragma unroll
;             for (int j = 0; j < 4; ++j) { e[4 * f + j] = fast_exp2(fmaf(s[2 * p + f][j], 1.4426950408889634f, -mxl)); sum += e[4 * f + j]; }
;         u32x4 pw; pw.x = cvt_pk_bf16(e[0], e[1]); pw.y = cvt_pk_bf16(e[2], e[3]); pw.z = cvt_pk_bf16(e[4], e[5]); pw.w = cvt_pk_bf16(e[6], e[7]);
;         pb[p] = __builtin_bit_cast(bf16x8, pw); }
	v_fmamk_f32 v94, v195, 0x3fb8aa3b, v106
	v_add_f32_e32 v91, v90, v96
	v_exp_f32_e32 v96, v94
	v_fmamk_f32 v94, v140, 0x3fb8aa3b, v106
	v_add_f32_e32 v91, v92, v91
	v_exp_f32_e32 v97, v94
	v_fmamk_f32 v94, v199, 0x3fb8aa3b, v106
	v_add_f32_e32 v91, v93, v91
	v_exp_f32_e32 v98, v94
	v_fmamk_f32 v94, v197, 0x3fb8aa3b, v106
	v_add_f32_e32 v91, v95, v91
	v_exp_f32_e32 v99, v94
	v_cvt_pk_bf16_f32 v94, v90, v92
	v_fmamk_f32 v90, v198, 0x3fb8aa3b, v106
	v_add_f32_e32 v91, v96, v91
	v_exp_f32_e32 v90, v90
	v_fmamk_f32 v92, v196, 0x3fb8aa3b, v106
	v_add_f32_e32 v91, v97, v91
	v_cvt_pk_bf16_f32 v95, v93, v95
	v_exp_f32_e32 v92, v92
	v_fmamk_f32 v93, v202, 0x3fb8aa3b, v106
	v_add_f32_e32 v91, v98, v91
	v_cvt_pk_bf16_f32 v96, v96, v97
	v_cvt_pk_bf16_f32 v97, v98, v99
	v_exp_f32_e32 v93, v93
	v_fmamk_f32 v98, v200, 0x3fb8aa3b, v106
	v_add_f32_e32 v91, v99, v91
	v_exp_f32_e32 v98, v98
	v_fmamk_f32 v99, v203, 0x3fb8aa3b, v106
	v_add_f32_e32 v91, v90, v91
	v_exp_f32_e32 v99, v99
	v_fmamk_f32 v100, v201, 0x3fb8aa3b, v106
	v_add_f32_e32 v91, v92, v91
	v_exp_f32_e32 v100, v100
	v_fmamk_f32 v101, v205, 0x3fb8aa3b, v106
	v_add_f32_e32 v91, v93, v91
	v_exp_f32_e32 v101, v101
	v_fmamk_f32 v102, v204, 0x3fb8aa3b, v106
	v_add_f32_e32 v91, v98, v91
	v_exp_f32_e32 v105, v102
	v_fmamk_f32 v2, v2, 0x3fb8aa3b, v106
	v_add_f32_e32 v91, v99, v91
	v_exp_f32_e32 v2, v2
	v_fmamk_f32 v3, v3, 0x3fb8aa3b, v106
	v_add_f32_e32 v91, v100, v91
	v_exp_f32_e32 v3, v3
	v_fmamk_f32 v4, v4, 0x3fb8aa3b, v106
	v_add_f32_e32 v91, v101, v91
	v_exp_f32_e32 v4, v4
	v_fmamk_f32 v5, v5, 0x3fb8aa3b, v106
	v_add_f32_e32 v91, v105, v91
	v_exp_f32_e32 v5, v5
	v_fmamk_f32 v10, v10, 0x3fb8aa3b, v106
	v_cvt_pk_bf16_f32 v102, v90, v92
	v_add_f32_e32 v90, v2, v91
	v_exp_f32_e32 v10, v10
	v_fmamk_f32 v11, v11, 0x3fb8aa3b, v106
	v_add_f32_e32 v90, v3, v90
	v_exp_f32_e32 v11, v11
	v_fmamk_f32 v12, v12, 0x3fb8aa3b, v106
	v_add_f32_e32 v90, v4, v90
	v_exp_f32_e32 v12, v12
	v_fmamk_f32 v13, v13, 0x3fb8aa3b, v106
	v_cvt_pk_bf16_f32 v103, v93, v98
	v_cvt_pk_bf16_f32 v104, v99, v100
	v_cvt_pk_bf16_f32 v105, v101, v105
	v_add_f32_e32 v90, v5, v90
	v_exp_f32_e32 v13, v13
	v_cvt_pk_bf16_f32 v98, v2, v3
	v_fmamk_f32 v2, v6, 0x3fb8aa3b, v106
	v_add_f32_e32 v90, v10, v90
	v_cvt_pk_bf16_f32 v99, v4, v5
	v_exp_f32_e32 v2, v2
	v_fmamk_f32 v4, v7, 0x3fb8aa3b, v106
	v_add_f32_e32 v90, v11, v90
	v_exp_f32_e32 v4, v4
	v_fmamk_f32 v5, v8, 0x3fb8aa3b, v106
	v_add_f32_e32 v90, v12, v90
	v_exp_f32_e32 v5, v5
	v_fmamk_f32 v6, v9, 0x3fb8aa3b, v106
	v_add_f32_e32 v90, v13, v90
	v_exp_f32_e32 v6, v6
	v_fmamk_f32 v7, v18, 0x3fb8aa3b, v106
	v_add_f32_e32 v3, v2, v90
	v_exp_f32_e32 v7, v7
	v_fmamk_f32 v8, v19, 0x3fb8aa3b, v106
	v_add_f32_e32 v3, v4, v3
	v_exp_f32_e32 v8, v8
	v_fmamk_f32 v9, v20, 0x3fb8aa3b, v106
	v_cvt_pk_bf16_f32 v100, v10, v11
	v_add_f32_e32 v3, v5, v3
	v_exp_f32_e32 v9, v9
	v_fmamk_f32 v10, v21, 0x3fb8aa3b, v106
	v_cvt_pk_bf16_f32 v101, v12, v13
	v_add_f32_e32 v3, v6, v3
	v_exp_f32_e32 v10, v10
	v_cvt_pk_bf16_f32 v90, v2, v4
	v_fmamk_f32 v2, v14, 0x3fb8aa3b, v106
	v_add_f32_e32 v3, v7, v3
	v_exp_f32_e32 v2, v2
	v_fmamk_f32 v4, v15, 0x3fb8aa3b, v106
	v_add_f32_e32 v3, v8, v3
	v_cvt_pk_bf16_f32 v91, v5, v6
	v_exp_f32_e32 v4, v4
	v_fmamk_f32 v5, v16, 0x3fb8aa3b, v106
	v_add_f32_e32 v3, v9, v3
	v_exp_f32_e32 v5, v5
	v_fmamk_f32 v6, v17, 0x3fb8aa3b, v106
	v_add_f32_e32 v3, v10, v3
	v_cvt_pk_bf16_f32 v92, v7, v8
	v_exp_f32_e32 v6, v6
	v_fmamk_f32 v7, v26, 0x3fb8aa3b, v106
	v_add_f32_e32 v3, v2, v3
	v_exp_f32_e32 v7, v7
	v_fmamk_f32 v8, v27, 0x3fb8aa3b, v106
	v_cvt_pk_bf16_f32 v93, v9, v10
	v_add_f32_e32 v3, v4, v3
	v_exp_f32_e32 v8, v8
	v_fmamk_f32 v9, v28, 0x3fb8aa3b, v106
	v_add_f32_e32 v3, v5, v3
	v_exp_f32_e32 v9, v9
	v_fmamk_f32 v10, v29, 0x3fb8aa3b, v106
	v_add_f32_e32 v3, v6, v3
	v_exp_f32_e32 v10, v10
	v_cvt_pk_bf16_f32 v26, v2, v4
	v_fmamk_f32 v2, v22, 0x3fb8aa3b, v106
	v_add_f32_e32 v3, v7, v3
	v_exp_f32_e32 v2, v2
	v_fmamk_f32 v4, v23, 0x3fb8aa3b, v106
	v_add_f32_e32 v3, v8, v3
	v_cvt_pk_bf16_f32 v27, v5, v6
	v_exp_f32_e32 v4, v4
	v_fmamk_f32 v5, v24, 0x3fb8aa3b, v106
	v_add_f32_e32 v3, v9, v3
	v_exp_f32_e32 v5, v5
	v_fmamk_f32 v6, v25, 0x3fb8aa3b, v106
	v_add_f32_e32 v3, v10, v3
	v_cvt_pk_bf16_f32 v28, v7, v8
	v_exp_f32_e32 v6, v6
	v_fmamk_f32 v7, v34, 0x3fb8aa3b, v106
	v_add_f32_e32 v3, v2, v3
	v_exp_f32_e32 v7, v7
	v_fmamk_f32 v8, v35, 0x3fb8aa3b, v106
	v_cvt_pk_bf16_f32 v29, v9, v10
	v_add_f32_e32 v3, v4, v3
	v_exp_f32_e32 v8, v8
	v_fmamk_f32 v9, v36, 0x3fb8aa3b, v106
	v_add_f32_e32 v3, v5, v3
	v_exp_f32_e32 v9, v9
	v_fmamk_f32 v10, v37, 0x3fb8aa3b, v106
	v_add_f32_e32 v3, v6, v3
	v_exp_f32_e32 v13, v10
	v_cvt_pk_bf16_f32 v10, v2, v4
	v_fmamk_f32 v2, v30, 0x3fb8aa3b, v106
	v_add_f32_e32 v3, v7, v3
	v_exp_f32_e32 v2, v2
	v_fmamk_f32 v4, v31, 0x3fb8aa3b, v106
	v_add_f32_e32 v3, v8, v3
	v_cvt_pk_bf16_f32 v11, v5, v6
	v_exp_f32_e32 v4, v4
	v_fmamk_f32 v5, v32, 0x3fb8aa3b, v106
	v_add_f32_e32 v3, v9, v3
	v_exp_f32_e32 v5, v5
	v_fmamk_f32 v6, v33, 0x3fb8aa3b, v106
	v_add_f32_e32 v3, v13, v3
	v_cvt_pk_bf16_f32 v12, v7, v8
	v_exp_f32_e32 v6, v6
	v_fmamk_f32 v7, v42, 0x3fb8aa3b, v106
	v_add_f32_e32 v3, v2, v3
	v_exp_f32_e32 v7, v7
	v_fmamk_f32 v8, v43, 0x3fb8aa3b, v106
	v_cvt_pk_bf16_f32 v13, v9, v13
	v_add_f32_e32 v3, v4, v3
	v_exp_f32_e32 v8, v8
	v_fmamk_f32 v9, v44, 0x3fb8aa3b, v106
	v_add_f32_e32 v3, v5, v3
	v_exp_f32_e32 v9, v9
	v_fmamk_f32 v14, v45, 0x3fb8aa3b, v106
	v_add_f32_e32 v3, v6, v3
	v_exp_f32_e32 v14, v14
	v_add_f32_e32 v3, v7, v3
	v_add_f32_e32 v3, v8, v3
	v_add_f32_e32 v3, v9, v3
	v_add_f32_e32 v15, v14, v3
	v_cvt_pk_bf16_f32 v2, v2, v4
	v_cvt_pk_bf16_f32 v3, v5, v6
	v_fmamk_f32 v6, v38, 0x3fb8aa3b, v106
; __device__ __forceinline__ unsigned cvt_pk_bf16(float lo, float hi) { unsigned r; asm volatile("v_cvt_pk_bf16_f32 %0, %1, %2" : "=v"(r) : "v"(lo), "v"(hi)); return r; }
; __device__ __forceinline__ float fast_exp2(float x) { return __builtin_amdgcn_exp2f(x); }
; #define ATT_VLOAD(buf, p) do { const bf16_t* vp_ = vloc + (size_t)((p) * 8 * NH) * 1024; \
;         _Pragma("unroll") for (int df = 0; df < 8; ++df) va[buf][df] = *(const bf16x8*)(vp_ + df * 128); } while (0)
; template <bool LOCAL>
; __device__ __forceinline__ void attn_unit(const bf16_t* Q, const bf16_t* KT, const bf16_t* VT, bf16_t* O, LAS unsigned char* lds, int b, int h, int r, int w, int tq, int lane) {
;     ...
;     for (int p = 0; p < NP; ++p) { float e[8];
; #pragma unroll
;         for (int f = 0; f < 2; ++f)
; #pragma unroll
;             for (int j = 0; j < 4; ++j) { e[4 * f + j] = fast_exp2(fmaf(s[2 * p + f][j], 1.4426950408889634f, -mxl)); sum += e[4 * f + j]; }
;         u32x4 pw; pw.x = cvt_pk_bf16(e[0], e[1]); pw.y = cvt_pk_bf16(e[2], e[3]); pw.z = cvt_pk_bf16(e[4], e[5]); pw.w = cvt_pk_bf16(e[6], e[7]);
;         pb[p] = __builtin_bit_cast(bf16x8, pw); }
;     sum += __shfl_xor(sum, 16); sum += __shfl_xor(sum, 32);
;     f32x4 o[8];
; #pragma unroll
;     for (int df = 0; df < 8; ++df) o[df] = (f32x4){0.f, 0.f, 0.f, 0.f};
;     if (LOCAL) {
;         const bf16_t* vloc = VT + ((size_t)(((rgl >> 3) + g) * NH + h)) * 1024 + q * 8;
;         bf16x8 va[2][8];
;     ...
;         ATT_VLOAD(0, 0);
; #pragma unroll
;         for (int p = 0; p < 8; ++p) {
;             __builtin_amdgcn_s_barrier();
;             if (p + 1 < 8) ATT_VLOAD((p + 1) & 1, p + 1);
;             __builtin_amdgcn_sched_barrier(0);
; #pragma unroll
;             for (int df = 0; df < 8; ++df) o[df] = __builtin_amdgcn_mfma_f32_16x16x32_bf16(va[p & 1][df], pb[p], o[df], 0, 0, 0);
;             __builtin_amdgcn_sched_barrier(0);
;         }
	v_exp_f32_e32 v6, v6
	v_cvt_pk_bf16_f32 v4, v7, v8
	v_fmamk_f32 v8, v39, 0x3fb8aa3b, v106
	v_cvt_pk_bf16_f32 v5, v9, v14
	v_exp_f32_e32 v8, v8
	v_fmamk_f32 v9, v40, 0x3fb8aa3b, v106
	v_exp_f32_e32 v9, v9
	v_fmamk_f32 v14, v41, 0x3fb8aa3b, v106
	v_add_f32_e32 v7, v6, v15
	v_exp_f32_e32 v14, v14
	v_fmamk_f32 v15, v50, 0x3fb8aa3b, v106
	v_exp_f32_e32 v15, v15
	v_fmamk_f32 v16, v51, 0x3fb8aa3b, v106
	v_add_f32_e32 v7, v8, v7
	v_exp_f32_e32 v16, v16
	v_fmamk_f32 v17, v52, 0x3fb8aa3b, v106
	v_add_f32_e32 v7, v9, v7
	v_exp_f32_e32 v17, v17
	v_fmamk_f32 v18, v53, 0x3fb8aa3b, v106
	v_add_f32_e32 v7, v14, v7
	v_exp_f32_e32 v18, v18
	v_add_f32_e32 v7, v15, v7
	v_add_f32_e32 v7, v16, v7
	v_add_f32_e32 v7, v17, v7
	v_add_f32_e32 v19, v18, v7
	v_cvt_pk_bf16_f32 v6, v6, v8
	v_cvt_pk_bf16_f32 v7, v9, v14
	v_fmamk_f32 v14, v46, 0x3fb8aa3b, v106
	v_exp_f32_e32 v14, v14
	v_cvt_pk_bf16_f32 v8, v15, v16
	v_fmamk_f32 v16, v47, 0x3fb8aa3b, v106
	v_cvt_pk_bf16_f32 v9, v17, v18
	v_exp_f32_e32 v16, v16
	v_fmamk_f32 v17, v48, 0x3fb8aa3b, v106
	v_exp_f32_e32 v17, v17
	v_fmamk_f32 v18, v49, 0x3fb8aa3b, v106
	v_add_f32_e32 v15, v14, v19
	v_exp_f32_e32 v18, v18
	v_fmamk_f32 v19, v58, 0x3fb8aa3b, v106
	v_exp_f32_e32 v19, v19
	v_fmamk_f32 v20, v59, 0x3fb8aa3b, v106
	v_add_f32_e32 v15, v16, v15
	v_exp_f32_e32 v20, v20
	v_fmamk_f32 v21, v60, 0x3fb8aa3b, v106
	v_add_f32_e32 v15, v17, v15
	v_exp_f32_e32 v21, v21
	v_fmamk_f32 v22, v61, 0x3fb8aa3b, v106
	v_add_f32_e32 v15, v18, v15
	v_exp_f32_e32 v22, v22
	v_add_f32_e32 v15, v19, v15
	v_add_f32_e32 v15, v20, v15
	v_add_f32_e32 v15, v21, v15
	v_add_f32_e32 v23, v22, v15
	v_cvt_pk_bf16_f32 v14, v14, v16
	v_cvt_pk_bf16_f32 v15, v17, v18
	v_fmamk_f32 v18, v54, 0x3fb8aa3b, v106
	v_exp_f32_e32 v18, v18
	v_cvt_pk_bf16_f32 v16, v19, v20
	v_fmamk_f32 v20, v55, 0x3fb8aa3b, v106
	v_cvt_pk_bf16_f32 v17, v21, v22
	v_exp_f32_e32 v20, v20
	v_fmamk_f32 v21, v56, 0x3fb8aa3b, v106
	v_exp_f32_e32 v21, v21
	v_fmamk_f32 v22, v57, 0x3fb8aa3b, v106
	v_add_f32_e32 v19, v18, v23
	v_exp_f32_e32 v22, v22
	v_fmamk_f32 v23, v62, 0x3fb8aa3b, v106
	v_exp_f32_e32 v23, v23
	v_fmamk_f32 v24, v63, 0x3fb8aa3b, v106
	v_add_f32_e32 v19, v20, v19
	v_exp_f32_e32 v24, v24
	v_fmamk_f32 v25, v64, 0x3fb8aa3b, v106
	v_add_f32_e32 v19, v21, v19
	v_exp_f32_e32 v25, v25
	v_fmac_f32_e32 v106, 0x3fb8aa3b, v65
	v_add_f32_e32 v19, v22, v19
	v_exp_f32_e32 v30, v106
	v_add_f32_e32 v19, v23, v19
	v_add_f32_e32 v19, v24, v19
	v_add_f32_e32 v19, v25, v19
	v_add_f32_e32 v31, v30, v19
	v_cvt_pk_bf16_f32 v18, v18, v20
	v_cvt_pk_bf16_f32 v19, v21, v22
	ds_bpermute_b32 v22, v181, v31
	v_cvt_pk_bf16_f32 v20, v23, v24
	v_cvt_pk_bf16_f32 v21, v25, v30
	s_waitcnt lgkmcnt(0)
	v_add_f32_e32 v134, v31, v22
	v_add_u32_e32 v22, v194, v165
	v_lshl_or_b32 v22, v22, 4, s72
	v_ashrrev_i32_e32 v23, 31, v22
	v_lshlrev_b64 v[22:23], 11, v[22:23]
	v_lshl_add_u64 v[132:133], v[148:149], 0, v[22:23]
	ds_bpermute_b32 v135, v182, v134
	s_cmp_eq_u32 s53, 0
	s_cbranch_scc0 .Lrg_v_B
	s_waitcnt vmcnt(6)
	s_barrier
	s_add_i32 m0, s59, 57344
	v_add_co_u32_e32 v222, vcc, s2, v226
	s_nop 1
	v_addc_co_u32_e32 v223, vcc, 0, v227, vcc
	global_load_lds_dwordx4 v[222:223], off
	ds_read_b128 v[106:109], v219 offset:0
	ds_read_b128 v[110:113], v219 offset:256
	ds_read_b128 v[114:117], v219 offset:512
	ds_read_b128 v[118:121], v219 offset:768
	s_waitcnt lgkmcnt(3)
	v_mfma_f32_16x16x32_bf16 v[22:25], v[106:109], v[66:69], 0
	s_waitcnt lgkmcnt(2)
	v_mfma_f32_16x16x32_bf16 v[30:33], v[110:113], v[66:69], 0
	s_waitcnt lgkmcnt(1)
	v_mfma_f32_16x16x32_bf16 v[34:37], v[114:117], v[66:69], 0
	s_waitcnt lgkmcnt(0)
	v_mfma_f32_16x16x32_bf16 v[38:41], v[118:121], v[66:69], 0
	s_waitcnt vmcnt(6)
	s_barrier
	s_add_i32 m0, s59, 0
	v_add_co_u32_e32 v222, vcc, s60, v220
	s_nop 1
	v_addc_co_u32_e32 v223, vcc, 0, v221, vcc
	global_load_lds_dwordx4 v[222:223], off
	ds_read_b128 v[122:125], v219 offset:8192
	ds_read_b128 v[126:129], v219 offset:8448
	ds_read_b128 v[58:61], v219 offset:8704
	ds_read_b128 v[62:65], v219 offset:8960
	s_waitcnt lgkmcnt(3)
	v_mfma_f32_16x16x32_bf16 v[42:45], v[122:125], v[66:69], 0
	s_waitcnt lgkmcnt(2)
	v_mfma_f32_16x16x32_bf16 v[46:49], v[126:129], v[66:69], 0
	s_waitcnt lgkmcnt(1)
	v_mfma_f32_16x16x32_bf16 v[50:53], v[58:61], v[66:69], 0
	s_waitcnt lgkmcnt(0)
	v_mfma_f32_16x16x32_bf16 v[54:57], v[62:65], v[66:69], 0
	s_waitcnt vmcnt(6)
	s_barrier
	s_add_i32 m0, s59, 8192
	v_add_co_u32_e32 v222, vcc, s60, v226
	s_nop 1
	v_addc_co_u32_e32 v223, vcc, 0, v227, vcc
	global_load_lds_dwordx4 v[222:223], off
	ds_read_b128 v[106:109], v219 offset:16384
	ds_read_b128 v[110:113], v219 offset:16640
	ds_read_b128 v[114:117], v219 offset:16896
	ds_read_b128 v[118:121], v219 offset:17152
	s_waitcnt lgkmcnt(3)
	v_mfma_f32_16x16x32_bf16 v[22:25], v[106:109], v[70:73], v[22:25]
	s_waitcnt lgkmcnt(2)
	v_mfma_f32_16x16x32_bf16 v[30:33], v[110:113], v[70:73], v[30:33]
	s_waitcnt lgkmcnt(1)
	v_mfma_f32_16x16x32_bf16 v[34:37], v[114:117], v[70:73], v[34:37]
	s_waitcnt lgkmcnt(0)
	v_mfma_f32_16x16x32_bf16 v[38:41], v[118:121], v[70:73], v[38:41]
	s_waitcnt vmcnt(6)
	s_barrier
; #define ATT_VLOAD(buf, p) do { const bf16_t* vp_ = vloc + (size_t)((p) * 8 * NH) * 1024; \
;         _Pragma("unroll") for (int df = 0; df < 8; ++df) va[buf][df] = *(const bf16x8*)(vp_ + df * 128); } while (0)
; template <bool LOCAL>
; __device__ __forceinline__ void attn_unit(const bf16_t* Q, const bf16_t* KT, const bf16_t* VT, bf16_t* O, LAS unsigned char* lds, int b, int h, int r, int w, int tq, int lane) {
;     ...
;     if (LOCAL) {
;         const bf16_t* vloc = VT + ((size_t)(((rgl >> 3) + g) * NH + h)) * 1024 + q * 8;
;         bf16x8 va[2][8];
;     ...
;         ATT_VLOAD(0, 0);
; #pragma unroll
;         for (int p = 0; p < 8; ++p) {
;             __builtin_amdgcn_s_barrier();
;             if (p + 1 < 8) ATT_VLOAD((p + 1) & 1, p + 1);
;             __builtin_amdgcn_sched_barrier(0);
; #pragma unroll
;             for (int df = 0; df < 8; ++df) o[df] = __builtin_amdgcn_mfma_f32_16x16x32_bf16(va[p & 1][df], pb[p], o[df], 0, 0, 0);
;             __builtin_amdgcn_sched_barrier(0);
;         }
	s_add_i32 m0, s59, 16384
	v_add_co_u32_e32 v222, vcc, s61, v220
	s_nop 1
	v_addc_co_u32_e32 v223, vcc, 0, v221, vcc
	global_load_lds_dwordx4 v[222:223], off
	ds_read_b128 v[122:125], v219 offset:24576
	ds_read_b128 v[126:129], v219 offset:24832
	ds_read_b128 v[58:61], v219 offset:25088
	ds_read_b128 v[62:65], v219 offset:25344
	s_waitcnt lgkmcnt(3)
	v_mfma_f32_16x16x32_bf16 v[42:45], v[122:125], v[70:73], v[42:45]
	s_waitcnt lgkmcnt(2)
	v_mfma_f32_16x16x32_bf16 v[46:49], v[126:129], v[70:73], v[46:49]
	s_waitcnt lgkmcnt(1)
	v_mfma_f32_16x16x32_bf16 v[50:53], v[58:61], v[70:73], v[50:53]
	s_waitcnt lgkmcnt(0)
	v_mfma_f32_16x16x32_bf16 v[54:57], v[62:65], v[70:73], v[54:57]
	s_waitcnt vmcnt(6)
	s_barrier
	s_add_i32 m0, s59, 24576
	v_add_co_u32_e32 v222, vcc, s61, v226
	s_nop 1
	v_addc_co_u32_e32 v223, vcc, 0, v227, vcc
	global_load_lds_dwordx4 v[222:223], off
	ds_read_b128 v[106:109], v219 offset:32768
	ds_read_b128 v[110:113], v219 offset:33024
	ds_read_b128 v[114:117], v219 offset:33280
	ds_read_b128 v[118:121], v219 offset:33536
	s_waitcnt lgkmcnt(3)
	v_mfma_f32_16x16x32_bf16 v[22:25], v[106:109], v[74:77], v[22:25]
	s_waitcnt lgkmcnt(2)
	v_mfma_f32_16x16x32_bf16 v[30:33], v[110:113], v[74:77], v[30:33]
	s_waitcnt lgkmcnt(1)
	v_mfma_f32_16x16x32_bf16 v[34:37], v[114:117], v[74:77], v[34:37]
	s_waitcnt lgkmcnt(0)
	v_mfma_f32_16x16x32_bf16 v[38:41], v[118:121], v[74:77], v[38:41]
	s_waitcnt vmcnt(6)
	s_barrier
	s_add_i32 m0, s59, 32768
	v_add_co_u32_e32 v222, vcc, s17, v220
	s_nop 1
	v_addc_co_u32_e32 v223, vcc, 0, v221, vcc
	global_load_lds_dwordx4 v[222:223], off
	ds_read_b128 v[122:125], v219 offset:40960
	ds_read_b128 v[126:129], v219 offset:41216
	ds_read_b128 v[58:61], v219 offset:41472
	ds_read_b128 v[62:65], v219 offset:41728
	s_waitcnt lgkmcnt(3)
	v_mfma_f32_16x16x32_bf16 v[42:45], v[122:125], v[74:77], v[42:45]
	s_waitcnt lgkmcnt(2)
	v_mfma_f32_16x16x32_bf16 v[46:49], v[126:129], v[74:77], v[46:49]
	s_waitcnt lgkmcnt(1)
	v_mfma_f32_16x16x32_bf16 v[50:53], v[58:61], v[74:77], v[50:53]
	s_waitcnt lgkmcnt(0)
	v_mfma_f32_16x16x32_bf16 v[54:57], v[62:65], v[74:77], v[54:57]
	s_waitcnt vmcnt(6)
	s_barrier
	s_add_i32 m0, s59, 40960
	v_add_co_u32_e32 v222, vcc, s17, v226
	s_nop 1
	v_addc_co_u32_e32 v223, vcc, 0, v227, vcc
	global_load_lds_dwordx4 v[222:223], off
	ds_read_b128 v[106:109], v219 offset:49152
	ds_read_b128 v[110:113], v219 offset:49408
	ds_read_b128 v[114:117], v219 offset:49664
	ds_read_b128 v[118:121], v219 offset:49920
	s_waitcnt lgkmcnt(3)
	v_mfma_f32_16x16x32_bf16 v[22:25], v[106:109], v[78:81], v[22:25]
	s_waitcnt lgkmcnt(2)
	v_mfma_f32_16x16x32_bf16 v[30:33], v[110:113], v[78:81], v[30:33]
	s_waitcnt lgkmcnt(1)
	v_mfma_f32_16x16x32_bf16 v[34:37], v[114:117], v[78:81], v[34:37]
	s_waitcnt lgkmcnt(0)
	v_mfma_f32_16x16x32_bf16 v[38:41], v[118:121], v[78:81], v[38:41]
	s_waitcnt vmcnt(6)
	s_barrier
	s_add_i32 m0, s59, 49152
	v_add_co_u32_e32 v222, vcc, s62, v220
	s_nop 1
	v_addc_co_u32_e32 v223, vcc, 0, v221, vcc
	global_load_lds_dwordx4 v[222:223], off
	ds_read_b128 v[122:125], v219 offset:57344
	ds_read_b128 v[126:129], v219 offset:57600
	ds_read_b128 v[58:61], v219 offset:57856
	ds_read_b128 v[62:65], v219 offset:58112
	s_waitcnt lgkmcnt(3)
	v_mfma_f32_16x16x32_bf16 v[42:45], v[122:125], v[78:81], v[42:45]
	s_waitcnt lgkmcnt(2)
	v_mfma_f32_16x16x32_bf16 v[46:49], v[126:129], v[78:81], v[46:49]
	s_waitcnt lgkmcnt(1)
	v_mfma_f32_16x16x32_bf16 v[50:53], v[58:61], v[78:81], v[50:53]
	s_waitcnt lgkmcnt(0)
	v_mfma_f32_16x16x32_bf16 v[54:57], v[62:65], v[78:81], v[54:57]
	s_waitcnt vmcnt(6)
	s_barrier
	s_add_i32 m0, s59, 57344
	v_add_co_u32_e32 v222, vcc, s62, v226
	s_nop 1
	v_addc_co_u32_e32 v223, vcc, 0, v227, vcc
	global_load_lds_dwordx4 v[222:223], off
	ds_read_b128 v[106:109], v219 offset:0
	ds_read_b128 v[110:113], v219 offset:256
	ds_read_b128 v[114:117], v219 offset:512
	ds_read_b128 v[118:121], v219 offset:768
	s_waitcnt lgkmcnt(3)
	v_mfma_f32_16x16x32_bf16 v[22:25], v[106:109], v[82:85], v[22:25]
	s_waitcnt lgkmcnt(2)
	v_mfma_f32_16x16x32_bf16 v[30:33], v[110:113], v[82:85], v[30:33]
	s_waitcnt lgkmcnt(1)
	v_mfma_f32_16x16x32_bf16 v[34:37], v[114:117], v[82:85], v[34:37]
	s_waitcnt lgkmcnt(0)
	v_mfma_f32_16x16x32_bf16 v[38:41], v[118:121], v[82:85], v[38:41]
	s_waitcnt vmcnt(6)
	s_barrier
	s_cmp_eq_u32 s73, 0
	s_cbranch_scc1 .Lrg_v_A_nd9
	s_add_i32 m0, s59, 0
	v_add_co_u32_e32 v222, vcc, s75, v220
	s_nop 1
	v_addc_co_u32_e32 v223, vcc, 0, v221, vcc
	global_load_lds_dwordx4 v[222:223], off

; #define LAS __attribute__((address_space(3)))
; template <bool LOCAL>
; __device__ __forceinline__ void attn_unit(const bf16_t* Q, const bf16_t* KT, const bf16_t* VT, bf16_t* O, LAS unsigned char* lds, int b, int h, int r, int w, int tq, int lane) {
;     ...
;     {
;         const LAS unsigned char* kl = lds + (q >> 2) * 2048 + (((q & 3) * 4 + g) ^ ((q >> 2) & 2)) * 16;
; #pragma unroll
;         for (int p = 0; p < 8; ++p)
; #pragma unroll
;             for (int f = 0; f < 2; ++f) { f32x4 a = {0.f, 0.f, 0.f, 0.f};
; #pragma unroll
;                 for (int ks = 0; ks < 4; ++ks) a = __builtin_amdgcn_mfma_f32_16x16x32_bf16(*(const LAS bf16x8*)(kl + p * 8192 + ks * 512 + f * 256), bq[ks], a, 0, 0, 0);
;                 s[2 * (CP + p) + f] = a; }
;     }
.Lrg_k_B_end:
.Lrg_k_done:
	s_barrier
	v_mov_b32_e32 v222, v236
	v_mov_b32_e32 v223, v237
	s_lshl_b32 s55, s57, 10
	s_add_i32 m0, s55, 65536
	s_nop 0
	global_load_lds_dwordx4 v[222:223], off
	v_add_co_u32_e32 v222, vcc, 0x20000, v222
	s_nop 1
	v_addc_co_u32_e32 v223, vcc, 0, v223, vcc
	s_add_i32 m0, s55, 73728
	s_nop 0
	global_load_lds_dwordx4 v[222:223], off
	v_add_co_u32_e32 v222, vcc, 0x20000, v222
	s_nop 1
	v_addc_co_u32_e32 v223, vcc, 0, v223, vcc
	s_add_i32 m0, s55, 81920
	s_nop 0
	global_load_lds_dwordx4 v[222:223], off
	v_add_co_u32_e32 v222, vcc, 0x20000, v222
	s_nop 1
	v_addc_co_u32_e32 v223, vcc, 0, v223, vcc
	s_add_i32 m0, s55, 90112
	s_nop 0
	global_load_lds_dwordx4 v[222:223], off
	v_add_co_u32_e32 v222, vcc, 0x20000, v222
	s_nop 1
	v_addc_co_u32_e32 v223, vcc, 0, v223, vcc
	s_add_i32 m0, s55, 98304
	s_nop 0
	global_load_lds_dwordx4 v[222:223], off
	v_add_co_u32_e32 v222, vcc, 0x20000, v222
	s_nop 1
	v_addc_co_u32_e32 v223, vcc, 0, v223, vcc
	s_add_i32 m0, s55, 106496
	s_nop 0
	global_load_lds_dwordx4 v[222:223], off
	v_add_co_u32_e32 v222, vcc, 0x20000, v222
	s_nop 1
	v_addc_co_u32_e32 v223, vcc, 0, v223, vcc
	s_add_i32 m0, s55, 114688
	s_nop 0
	global_load_lds_dwordx4 v[222:223], off
	v_add_co_u32_e32 v222, vcc, 0x20000, v222
	s_nop 1
	v_addc_co_u32_e32 v223, vcc, 0, v223, vcc
	s_add_i32 m0, s55, 122880
	s_nop 0
	global_load_lds_dwordx4 v[222:223], off
	s_nop 5
	s_waitcnt lgkmcnt(0)
	s_movk_i32 s4, 0x7c
	ds_read_b128 v[200:203], v169
	ds_read_b128 v[204:207], v169 offset:512
	ds_read_b128 v[208:211], v169 offset:1024
	ds_read_b128 v[212:215], v169 offset:1536
	ds_read_b128 v[216:219], v169 offset:256
	ds_read_b128 v[220:223], v169 offset:768
	ds_read_b128 v[224:227], v169 offset:1280
	ds_read_b128 v[228:231], v169 offset:1792
	s_waitcnt lgkmcnt(7)
	v_mfma_f32_16x16x32_bf16 v[2:5], v[200:203], v[138:141], 0
	ds_read_b128 v[200:203], v169 offset:8192
	s_waitcnt lgkmcnt(7)
	v_mfma_f32_16x16x32_bf16 v[2:5], v[204:207], v[134:137], v[2:5]
	ds_read_b128 v[204:207], v169 offset:8704
	s_waitcnt lgkmcnt(7)
	v_mfma_f32_16x16x32_bf16 v[2:5], v[208:211], v[130:133], v[2:5]
	ds_read_b128 v[208:211], v169 offset:9216
	s_waitcnt lgkmcnt(7)
	v_mfma_f32_16x16x32_bf16 v[2:5], v[212:215], v[62:65], v[2:5]
	ds_read_b128 v[212:215], v169 offset:9728
	s_waitcnt lgkmcnt(7)
	v_mfma_f32_16x16x32_bf16 v[6:9], v[216:219], v[138:141], 0
	ds_read_b128 v[216:219], v169 offset:8448
	s_waitcnt lgkmcnt(7)
	v_mfma_f32_16x16x32_bf16 v[6:9], v[220:223], v[134:137], v[6:9]
	ds_read_b128 v[220:223], v169 offset:8960
	s_waitcnt lgkmcnt(7)
	v_mfma_f32_16x16x32_bf16 v[6:9], v[224:227], v[130:133], v[6:9]
	ds_read_b128 v[224:227], v169 offset:9472
	s_waitcnt lgkmcnt(7)
	v_mfma_f32_16x16x32_bf16 v[10:13], v[228:231], v[62:65], v[6:9]
	ds_read_b128 v[228:231], v169 offset:9984
	s_waitcnt lgkmcnt(7)
	v_mfma_f32_16x16x32_bf16 v[6:9], v[200:203], v[138:141], 0
	ds_read_b128 v[200:203], v169 offset:16384
	s_waitcnt lgkmcnt(7)
	v_mfma_f32_16x16x32_bf16 v[6:9], v[204:207], v[134:137], v[6:9]
	ds_read_b128 v[204:207], v169 offset:16896
	s_waitcnt lgkmcnt(7)
	v_mfma_f32_16x16x32_bf16 v[6:9], v[208:211], v[130:133], v[6:9]
	ds_read_b128 v[208:211], v169 offset:17408
	s_waitcnt lgkmcnt(7)
	v_mfma_f32_16x16x32_bf16 v[6:9], v[212:215], v[62:65], v[6:9]
	ds_read_b128 v[212:215], v169 offset:17920
	s_waitcnt lgkmcnt(7)
	v_mfma_f32_16x16x32_bf16 v[14:17], v[216:219], v[138:141], 0
	ds_read_b128 v[216:219], v169 offset:16640
	s_waitcnt lgkmcnt(7)
	v_mfma_f32_16x16x32_bf16 v[14:17], v[220:223], v[134:137], v[14:17]
	ds_read_b128 v[220:223], v169 offset:17152
	s_waitcnt lgkmcnt(7)
	v_mfma_f32_16x16x32_bf16 v[14:17], v[224:227], v[130:133], v[14:17]
	ds_read_b128 v[224:227], v169 offset:17664
	s_waitcnt lgkmcnt(7)
	v_mfma_f32_16x16x32_bf16 v[18:21], v[228:231], v[62:65], v[14:17]
	ds_read_b128 v[228:231], v169 offset:18176
	s_waitcnt lgkmcnt(7)
	v_mfma_f32_16x16x32_bf16 v[14:17], v[200:203], v[138:141], 0
	ds_read_b128 v[200:203], v169 offset:24576
	s_waitcnt lgkmcnt(7)
	v_mfma_f32_16x16x32_bf16 v[14:17], v[204:207], v[134:137], v[14:17]
	ds_read_b128 v[204:207], v169 offset:25088
	s_waitcnt lgkmcnt(7)
	v_mfma_f32_16x16x32_bf16 v[14:17], v[208:211], v[130:133], v[14:17]
	ds_read_b128 v[208:211], v169 offset:25600
	s_waitcnt lgkmcnt(7)
	v_mfma_f32_16x16x32_bf16 v[14:17], v[212:215], v[62:65], v[14:17]
	ds_read_b128 v[212:215], v169 offset:26112
	s_waitcnt lgkmcnt(7)
	v_mfma_f32_16x16x32_bf16 v[22:25], v[216:219], v[138:141], 0
	ds_read_b128 v[216:219], v169 offset:24832
	s_waitcnt lgkmcnt(7)
	v_mfma_f32_16x16x32_bf16 v[22:25], v[220:223], v[134:137], v[22:25]
	ds_read_b128 v[220:223], v169 offset:25344
	s_waitcnt lgkmcnt(7)
	v_mfma_f32_16x16x32_bf16 v[22:25], v[224:227], v[130:133], v[22:25]
	ds_read_b128 v[224:227], v169 offset:25856
	s_waitcnt lgkmcnt(7)
	v_mfma_f32_16x16x32_bf16 v[26:29], v[228:231], v[62:65], v[22:25]
	ds_read_b128 v[228:231], v169 offset:26368
	s_waitcnt lgkmcnt(7)
	v_mfma_f32_16x16x32_bf16 v[22:25], v[200:203], v[138:141], 0
	ds_read_b128 v[200:203], v169 offset:32768
	s_waitcnt lgkmcnt(7)
	v_mfma_f32_16x16x32_bf16 v[22:25], v[204:207], v[134:137], v[22:25]
	ds_read_b128 v[204:207], v169 offset:33280
	s_waitcnt lgkmcnt(7)
	v_mfma_f32_16x16x32_bf16 v[22:25], v[208:211], v[130:133], v[22:25]
	ds_read_b128 v[208:211], v169 offset:33792
	s_waitcnt lgkmcnt(7)
	v_mfma_f32_16x16x32_bf16 v[22:25], v[212:215], v[62:65], v[22:25]
	ds_read_b128 v[212:215], v169 offset:34304
	s_waitcnt lgkmcnt(7)
	v_mfma_f32_16x16x32_bf16 v[30:33], v[216:219], v[138:141], 0
	ds_read_b128 v[216:219], v169 offset:33024
	s_waitcnt lgkmcnt(7)
; #define LAS __attribute__((address_space(3)))
; template <bool LOCAL>
; __device__ __forceinline__ void attn_unit(const bf16_t* Q, const bf16_t* KT, const bf16_t* VT, bf16_t* O, LAS unsigned char* lds, int b, int h, int r, int w, int tq, int lane) {
;     ...
;     {
;         const LAS unsigned char* kl = lds + (q >> 2) * 2048 + (((q & 3) * 4 + g) ^ ((q >> 2) & 2)) * 16;
; #pragma unroll
;         for (int p = 0; p < 8; ++p)
; #pragma unroll
;             for (int f = 0; f < 2; ++f) { f32x4 a = {0.f, 0.f, 0.f, 0.f};
; #pragma unroll
;                 for (int ks = 0; ks < 4; ++ks) a = __builtin_amdgcn_mfma_f32_16x16x32_bf16(*(const LAS bf16x8*)(kl + p * 8192 + ks * 512 + f * 256), bq[ks], a, 0, 0, 0);
;                 s[2 * (CP + p) + f] = a; }
;     }
	v_mfma_f32_16x16x32_bf16 v[30:33], v[220:223], v[134:137], v[30:33]
	ds_read_b128 v[220:223], v169 offset:33536
	s_waitcnt lgkmcnt(7)
	v_mfma_f32_16x16x32_bf16 v[30:33], v[224:227], v[130:133], v[30:33]
	ds_read_b128 v[224:227], v169 offset:34048
	s_waitcnt lgkmcnt(7)
	v_mfma_f32_16x16x32_bf16 v[34:37], v[228:231], v[62:65], v[30:33]
	ds_read_b128 v[228:231], v169 offset:34560
	s_waitcnt lgkmcnt(7)
	v_mfma_f32_16x16x32_bf16 v[30:33], v[200:203], v[138:141], 0
	ds_read_b128 v[200:203], v169 offset:40960
	s_waitcnt lgkmcnt(7)
	v_mfma_f32_16x16x32_bf16 v[30:33], v[204:207], v[134:137], v[30:33]
	ds_read_b128 v[204:207], v169 offset:41472
	s_waitcnt lgkmcnt(7)
	v_mfma_f32_16x16x32_bf16 v[30:33], v[208:211], v[130:133], v[30:33]
	ds_read_b128 v[208:211], v169 offset:41984
	s_waitcnt lgkmcnt(7)
	v_mfma_f32_16x16x32_bf16 v[30:33], v[212:215], v[62:65], v[30:33]
	ds_read_b128 v[212:215], v169 offset:42496
	s_waitcnt lgkmcnt(7)
	v_mfma_f32_16x16x32_bf16 v[38:41], v[216:219], v[138:141], 0
	ds_read_b128 v[216:219], v169 offset:41216
	s_waitcnt lgkmcnt(7)
	v_mfma_f32_16x16x32_bf16 v[38:41], v[220:223], v[134:137], v[38:41]
	ds_read_b128 v[220:223], v169 offset:41728
	s_waitcnt lgkmcnt(7)
	v_mfma_f32_16x16x32_bf16 v[38:41], v[224:227], v[130:133], v[38:41]
	ds_read_b128 v[224:227], v169 offset:42240
	s_waitcnt lgkmcnt(7)
	v_mfma_f32_16x16x32_bf16 v[42:45], v[228:231], v[62:65], v[38:41]
	ds_read_b128 v[228:231], v169 offset:42752
	s_waitcnt lgkmcnt(7)
	v_mfma_f32_16x16x32_bf16 v[38:41], v[200:203], v[138:141], 0
	ds_read_b128 v[200:203], v169 offset:49152
	s_waitcnt lgkmcnt(7)
	v_mfma_f32_16x16x32_bf16 v[38:41], v[204:207], v[134:137], v[38:41]
	ds_read_b128 v[204:207], v169 offset:49664
	s_waitcnt lgkmcnt(7)
	v_mfma_f32_16x16x32_bf16 v[38:41], v[208:211], v[130:133], v[38:41]
	ds_read_b128 v[208:211], v169 offset:50176
	s_waitcnt lgkmcnt(7)
	v_mfma_f32_16x16x32_bf16 v[38:41], v[212:215], v[62:65], v[38:41]
	ds_read_b128 v[212:215], v169 offset:50688
	s_waitcnt lgkmcnt(7)
	v_mfma_f32_16x16x32_bf16 v[46:49], v[216:219], v[138:141], 0
	ds_read_b128 v[216:219], v169 offset:49408
	s_waitcnt lgkmcnt(7)
	v_mfma_f32_16x16x32_bf16 v[46:49], v[220:223], v[134:137], v[46:49]
	ds_read_b128 v[220:223], v169 offset:49920
	s_waitcnt lgkmcnt(7)
	v_mfma_f32_16x16x32_bf16 v[46:49], v[224:227], v[130:133], v[46:49]
	ds_read_b128 v[224:227], v169 offset:50432
	s_waitcnt lgkmcnt(7)
	v_mfma_f32_16x16x32_bf16 v[50:53], v[228:231], v[62:65], v[46:49]
	ds_read_b128 v[228:231], v169 offset:50944
	s_waitcnt lgkmcnt(7)
	v_mfma_f32_16x16x32_bf16 v[46:49], v[200:203], v[138:141], 0
	ds_read_b128 v[200:203], v169 offset:57344
	s_waitcnt lgkmcnt(7)
	v_mfma_f32_16x16x32_bf16 v[46:49], v[204:207], v[134:137], v[46:49]
	ds_read_b128 v[204:207], v169 offset:57856
	s_waitcnt lgkmcnt(7)
	v_mfma_f32_16x16x32_bf16 v[46:49], v[208:211], v[130:133], v[46:49]
	ds_read_b128 v[208:211], v169 offset:58368
	s_waitcnt lgkmcnt(7)
	v_mfma_f32_16x16x32_bf16 v[46:49], v[212:215], v[62:65], v[46:49]
	ds_read_b128 v[212:215], v169 offset:58880
	s_waitcnt lgkmcnt(7)
	v_mfma_f32_16x16x32_bf16 v[54:57], v[216:219], v[138:141], 0
	ds_read_b128 v[216:219], v169 offset:57600
	s_waitcnt lgkmcnt(7)
	v_mfma_f32_16x16x32_bf16 v[54:57], v[220:223], v[134:137], v[54:57]
	ds_read_b128 v[220:223], v169 offset:58112
	s_waitcnt lgkmcnt(7)
	v_mfma_f32_16x16x32_bf16 v[54:57], v[224:227], v[130:133], v[54:57]
	ds_read_b128 v[224:227], v169 offset:58624
	s_waitcnt lgkmcnt(7)
	v_mfma_f32_16x16x32_bf16 v[58:61], v[228:231], v[62:65], v[54:57]
	ds_read_b128 v[228:231], v169 offset:59136
	s_waitcnt lgkmcnt(7)
	v_mfma_f32_16x16x32_bf16 v[54:57], v[200:203], v[138:141], 0
	s_waitcnt lgkmcnt(6)
	v_mfma_f32_16x16x32_bf16 v[54:57], v[204:207], v[134:137], v[54:57]
	s_waitcnt lgkmcnt(5)
	v_mfma_f32_16x16x32_bf16 v[54:57], v[208:211], v[130:133], v[54:57]
	s_waitcnt lgkmcnt(4)
	v_mfma_f32_16x16x32_bf16 v[54:57], v[212:215], v[62:65], v[54:57]
	s_waitcnt lgkmcnt(3)
	v_mfma_f32_16x16x32_bf16 v[138:141], v[216:219], v[138:141], 0
	s_waitcnt lgkmcnt(2)
	v_mfma_f32_16x16x32_bf16 v[134:137], v[220:223], v[134:137], v[138:141]
	s_waitcnt lgkmcnt(1)
	v_mfma_f32_16x16x32_bf16 v[130:133], v[224:227], v[130:133], v[134:137]
	s_waitcnt lgkmcnt(0)
	v_mfma_f32_16x16x32_bf16 v[62:65], v[228:231], v[62:65], v[130:133]
	s_nop 7
	s_nop 2
	s_barrier
; #define LAS __attribute__((address_space(3)))
; #define ATT_VLOAD(buf, p) do { const bf16_t* vp_ = vloc + (size_t)((p) * 8 * NH) * 1024; \
;         _Pragma("unroll") for (int df = 0; df < 8; ++df) va[buf][df] = *(const bf16x8*)(vp_ + df * 128); } while (0)
; template <bool LOCAL>
; __device__ __forceinline__ void attn_unit(const bf16_t* Q, const bf16_t* KT, const bf16_t* VT, bf16_t* O, LAS unsigned char* lds, int b, int h, int r, int w, int tq, int lane) {
;     ...
;     if (LOCAL) {
;         const int c = 16 * w + q; int cs = c - 8; cs = cs < 0 ? 0 : (cs > 48 ? 48 : cs);
;         const LAS float* rp = (const LAS float*)(lds + LDS_MISC + 1024);
; #pragma unroll
;         for (int p = 0; p < 8; ++p) { const int ro = (rs + p - r + 7) * 31;
; #pragma unroll
;             for (int f = 0; f < 2; ++f)
; #pragma unroll
;                 for (int j = 0; j < 4; ++j) { const int kc = ws + 8 * g + 4 * f + j; const bool valid = (kc >= cs) && (kc < cs + 16);
;                     int rel = kc - c + 15; rel = rel < 0 ? 0 : (rel > 30 ? 30 : rel);
;                     const float bias = rp[ro + rel];
;                     s[p * 2 + f][j] = valid ? s[p * 2 + f][j] + bias : -INFINITY; } }
;     }
;     ...
;         const bf16_t* vloc = VT + ((size_t)(((rgl >> 3) + g) * NH + h)) * 1024 + q * 8;
;         bf16x8 va[2][8];
;     ...
;         ATT_VLOAD(0, 0);
	s_lshl_b32 s54, s57, 10
	s_add_i32 s59, s54, 0x0
	v_lshlrev_b32_e32 v218, 4, v164
	v_add_u32_e32 v218, s28, v218
	ds_read_b64 v[220:221], v241 offset:192
	s_waitcnt lgkmcnt(0)
	v_add_co_u32_e32 v220, vcc, 0x24300000, v220
	s_nop 1
	v_addc_co_u32_e32 v221, vcc, 0, v221, vcc
	v_add_co_u32_e32 v220, vcc, v220, v218
	s_nop 1
	v_addc_co_u32_e32 v221, vcc, 0, v221, vcc
	v_add_co_u32_e32 v226, vcc, 0x400, v220
	s_nop 1
	v_addc_co_u32_e32 v227, vcc, 0, v221, vcc
	s_and_b32 s55, s57, 3
	s_lshl_b32 s55, s55, 1
	s_add_i32 s55, s55, -1
	s_max_i32 s55, s55, 0
	s_min_i32 s55, s55, 4
	v_add_u32_e32 v219, s55, v165
	v_lshlrev_b32_e32 v224, 4, v166
	v_lshl_add_u32 v219, v219, 10, v224
	s_add_i32 m0, s59, 0
	s_nop 0
	global_load_lds_dwordx4 v[220:221], off
	s_add_i32 m0, s59, 8192
	s_nop 0
	global_load_lds_dwordx4 v[226:227], off
	s_add_i32 m0, s59, 16384
	v_add_co_u32_e32 v222, vcc, s6, v220
	s_nop 1
	v_addc_co_u32_e32 v223, vcc, 0, v221, vcc
	global_load_lds_dwordx4 v[222:223], off
	s_add_i32 m0, s59, 24576
	v_add_co_u32_e32 v222, vcc, s6, v226
	s_nop 1
	v_addc_co_u32_e32 v223, vcc, 0, v227, vcc
	global_load_lds_dwordx4 v[222:223], off
	s_add_i32 m0, s59, 32768
	v_add_co_u32_e32 v222, vcc, s7, v220
	s_nop 1
	v_addc_co_u32_e32 v223, vcc, 0, v221, vcc
	global_load_lds_dwordx4 v[222:223], off
	s_add_i32 m0, s59, 40960
	v_add_co_u32_e32 v222, vcc, s7, v226
	s_nop 1
	v_addc_co_u32_e32 v223, vcc, 0, v227, vcc
	global_load_lds_dwordx4 v[222:223], off
	s_add_i32 m0, s59, 49152
	v_add_co_u32_e32 v222, vcc, s2, v220
	s_nop 1
	v_addc_co_u32_e32 v223, vcc, 0, v221, vcc
	global_load_lds_dwordx4 v[222:223], off
	v_mul_lo_u32 v130, v195, s4
	v_add_u32_e32 v130, 0, v130
	v_add_u32_e32 v135, 0x20400, v130
	v_lshl_add_u32 v130, v170, 2, v135
	v_lshl_add_u32 v131, v171, 2, v135
	v_lshl_add_u32 v201, v172, 2, v135
	v_lshl_add_u32 v203, v173, 2, v135
	v_lshl_add_u32 v204, v174, 2, v135
	v_lshl_add_u32 v205, v175, 2, v135
	v_lshl_add_u32 v206, v176, 2, v135
	v_lshl_add_u32 v207, v177, 2, v135
	v_mov_b32_e32 v246, 0xff800000
	ds_read_b32 v208, v130 offset:928
	ds_read_b32 v209, v131 offset:928
	ds_read_b32 v210, v201 offset:928
	ds_read_b32 v211, v203 offset:928
	ds_read_b32 v212, v204 offset:928
	ds_read_b32 v213, v205 offset:928
	ds_read_b32 v214, v206 offset:928
	ds_read_b32 v215, v207 offset:928
	ds_read_b32 v216, v130 offset:1052
	ds_read_b32 v217, v131 offset:1052
	ds_read_b32 v228, v201 offset:1052
	ds_read_b32 v229, v203 offset:1052
	ds_read_b32 v230, v204 offset:1052
	ds_read_b32 v231, v205 offset:1052
	ds_read_b32 v232, v206 offset:1052
	ds_read_b32 v233, v207 offset:1052
	s_waitcnt lgkmcnt(15)
	v_add_f32_e32 v208, v126, v208
	v_cndmask_b32_e64 v133, v246, v208, s[36:37]
	s_waitcnt lgkmcnt(14)
	v_add_f32_e32 v209, v127, v209
	v_cndmask_b32_e64 v132, v246, v209, s[46:47]
	s_waitcnt lgkmcnt(13)
	v_add_f32_e32 v210, v128, v210
	v_cndmask_b32_e64 v134, v246, v210, s[10:11]
	s_waitcnt lgkmcnt(12)
	v_add_f32_e32 v211, v129, v211
	v_cndmask_b32_e64 v126, v246, v211, s[14:15]
	s_waitcnt lgkmcnt(11)
	v_add_f32_e32 v212, v122, v212
	v_cndmask_b32_e64 v128, v246, v212, s[18:19]
	s_waitcnt lgkmcnt(10)
	v_add_f32_e32 v213, v123, v213
	v_cndmask_b32_e64 v127, v246, v213, s[20:21]
	s_waitcnt lgkmcnt(9)
	v_add_f32_e32 v214, v124, v214
	v_cndmask_b32_e64 v129, v246, v214, s[22:23]
	s_waitcnt lgkmcnt(8)
	v_add_f32_e32 v215, v125, v215
	v_cndmask_b32_e64 v123, v246, v215, s[0:1]
	s_waitcnt lgkmcnt(7)
	v_add_f32_e32 v216, v118, v216
	v_cndmask_b32_e64 v124, v246, v216, s[36:37]
	s_waitcnt lgkmcnt(6)
	v_add_f32_e32 v217, v119, v217
	v_cndmask_b32_e64 v122, v246, v217, s[46:47]
	s_waitcnt lgkmcnt(5)
	v_add_f32_e32 v228, v120, v228
	v_cndmask_b32_e64 v125, v246, v228, s[10:11]
	s_waitcnt lgkmcnt(4)
	v_add_f32_e32 v229, v121, v229
	v_cndmask_b32_e64 v118, v246, v229, s[14:15]
	s_waitcnt lgkmcnt(3)
	v_add_f32_e32 v230, v114, v230
	v_cndmask_b32_e64 v120, v246, v230, s[18:19]
	s_waitcnt lgkmcnt(2)
	v_add_f32_e32 v231, v115, v231
	v_cndmask_b32_e64 v119, v246, v231, s[20:21]
	s_waitcnt lgkmcnt(1)
	v_add_f32_e32 v232, v116, v232
	v_cndmask_b32_e64 v121, v246, v232, s[22:23]
	s_waitcnt lgkmcnt(0)
	v_add_f32_e32 v233, v117, v233
	v_cndmask_b32_e64 v115, v246, v233, s[0:1]
	ds_read_b32 v208, v130 offset:1176
	ds_read_b32 v209, v131 offset:1176
	ds_read_b32 v210, v201 offset:1176
	ds_read_b32 v211, v203 offset:1176
	ds_read_b32 v212, v204 offset:1176
	ds_read_b32 v213, v205 offset:1176
	ds_read_b32 v214, v206 offset:1176
	ds_read_b32 v215, v207 offset:1176
	ds_read_b32 v216, v130 offset:1300
	ds_read_b32 v217, v131 offset:1300
	ds_read_b32 v228, v201 offset:1300
	ds_read_b32 v229, v203 offset:1300
	ds_read_b32 v230, v204 offset:1300
	ds_read_b32 v231, v205 offset:1300
	ds_read_b32 v232, v206 offset:1300
	ds_read_b32 v233, v207 offset:1300
	s_waitcnt lgkmcnt(15)
	v_add_f32_e32 v208, v110, v208
	v_cndmask_b32_e64 v116, v246, v208, s[36:37]
	s_waitcnt lgkmcnt(14)
	v_add_f32_e32 v209, v111, v209
	v_cndmask_b32_e64 v114, v246, v209, s[46:47]
	s_waitcnt lgkmcnt(13)
	v_add_f32_e32 v210, v112, v210
	v_cndmask_b32_e64 v117, v246, v210, s[10:11]
	s_waitcnt lgkmcnt(12)
	v_add_f32_e32 v211, v113, v211
	v_cndmask_b32_e64 v110, v246, v211, s[14:15]
	s_waitcnt lgkmcnt(11)
	v_add_f32_e32 v212, v106, v212
	v_cndmask_b32_e64 v112, v246, v212, s[18:19]
	s_waitcnt lgkmcnt(10)
	v_add_f32_e32 v213, v107, v213
	v_cndmask_b32_e64 v111, v246, v213, s[20:21]
	s_waitcnt lgkmcnt(9)
; #define LAS __attribute__((address_space(3)))
; template <bool LOCAL>
; __device__ __forceinline__ void attn_unit(const bf16_t* Q, const bf16_t* KT, const bf16_t* VT, bf16_t* O, LAS unsigned char* lds, int b, int h, int r, int w, int tq, int lane) {
;     ...
;     if (LOCAL) {
;         const int c = 16 * w + q; int cs = c - 8; cs = cs < 0 ? 0 : (cs > 48 ? 48 : cs);
;         const LAS float* rp = (const LAS float*)(lds + LDS_MISC + 1024);
; #pragma unroll
;         for (int p = 0; p < 8; ++p) { const int ro = (rs + p - r + 7) * 31;
; #pragma unroll
;             for (int f = 0; f < 2; ++f)
; #pragma unroll
;                 for (int j = 0; j < 4; ++j) { const int kc = ws + 8 * g + 4 * f + j; const bool valid = (kc >= cs) && (kc < cs + 16);
;                     int rel = kc - c + 15; rel = rel < 0 ? 0 : (rel > 30 ? 30 : rel);
;                     const float bias = rp[ro + rel];
;                     s[p * 2 + f][j] = valid ? s[p * 2 + f][j] + bias : -INFINITY; } }
;     }
	v_add_f32_e32 v214, v108, v214
	v_cndmask_b32_e64 v135, v246, v214, s[22:23]
	s_waitcnt lgkmcnt(8)
	v_add_f32_e32 v215, v109, v215
	v_cndmask_b32_e64 v113, v246, v215, s[0:1]
	s_waitcnt lgkmcnt(7)
	v_add_f32_e32 v216, v102, v216
	v_cndmask_b32_e64 v108, v246, v216, s[36:37]
	s_waitcnt lgkmcnt(6)
	v_add_f32_e32 v217, v103, v217
	v_cndmask_b32_e64 v107, v246, v217, s[46:47]
	s_waitcnt lgkmcnt(5)
	v_add_f32_e32 v228, v104, v228
	v_cndmask_b32_e64 v109, v246, v228, s[10:11]
	s_waitcnt lgkmcnt(4)
	v_add_f32_e32 v229, v105, v229
	v_cndmask_b32_e64 v102, v246, v229, s[14:15]
	s_waitcnt lgkmcnt(3)
	v_add_f32_e32 v230, v98, v230
	v_cndmask_b32_e64 v104, v246, v230, s[18:19]
	s_waitcnt lgkmcnt(2)
	v_add_f32_e32 v231, v99, v231
	v_cndmask_b32_e64 v103, v246, v231, s[20:21]
	s_waitcnt lgkmcnt(1)
	v_add_f32_e32 v232, v100, v232
	v_cndmask_b32_e64 v105, v246, v232, s[22:23]
	s_waitcnt lgkmcnt(0)
	v_add_f32_e32 v233, v101, v233
	v_cndmask_b32_e64 v99, v246, v233, s[0:1]
	ds_read_b32 v208, v130 offset:1424
	ds_read_b32 v209, v131 offset:1424
	ds_read_b32 v210, v201 offset:1424
	ds_read_b32 v211, v203 offset:1424
	ds_read_b32 v212, v204 offset:1424
	ds_read_b32 v213, v205 offset:1424
	ds_read_b32 v214, v206 offset:1424
	ds_read_b32 v215, v207 offset:1424
	ds_read_b32 v216, v130 offset:1548
	ds_read_b32 v217, v131 offset:1548
	ds_read_b32 v228, v201 offset:1548
	ds_read_b32 v229, v203 offset:1548
	ds_read_b32 v230, v204 offset:1548
	ds_read_b32 v231, v205 offset:1548
	ds_read_b32 v232, v206 offset:1548
	ds_read_b32 v233, v207 offset:1548
	s_waitcnt lgkmcnt(15)
	v_add_f32_e32 v208, v94, v208
	v_cndmask_b32_e64 v100, v246, v208, s[36:37]
	s_waitcnt lgkmcnt(14)
	v_add_f32_e32 v209, v95, v209
	v_cndmask_b32_e64 v98, v246, v209, s[46:47]
	s_waitcnt lgkmcnt(13)
	v_add_f32_e32 v210, v96, v210
	v_cndmask_b32_e64 v101, v246, v210, s[10:11]
	s_waitcnt lgkmcnt(12)
	v_add_f32_e32 v211, v97, v211
	v_cndmask_b32_e64 v94, v246, v211, s[14:15]
	s_waitcnt lgkmcnt(11)
	v_add_f32_e32 v212, v90, v212
	v_cndmask_b32_e64 v96, v246, v212, s[18:19]
	s_waitcnt lgkmcnt(10)
	v_add_f32_e32 v213, v91, v213
	v_cndmask_b32_e64 v95, v246, v213, s[20:21]
	s_waitcnt lgkmcnt(9)
	v_add_f32_e32 v214, v92, v214
	v_cndmask_b32_e64 v97, v246, v214, s[22:23]
	s_waitcnt lgkmcnt(8)
	v_add_f32_e32 v215, v93, v215
	v_cndmask_b32_e64 v91, v246, v215, s[0:1]
	s_waitcnt lgkmcnt(7)
	v_add_f32_e32 v216, v86, v216
	v_cndmask_b32_e64 v92, v246, v216, s[36:37]
	s_waitcnt lgkmcnt(6)
	v_add_f32_e32 v217, v87, v217
	v_cndmask_b32_e64 v90, v246, v217, s[46:47]
	s_waitcnt lgkmcnt(5)
	v_add_f32_e32 v228, v88, v228
	v_cndmask_b32_e64 v93, v246, v228, s[10:11]
	s_waitcnt lgkmcnt(4)
	v_add_f32_e32 v229, v89, v229
	v_cndmask_b32_e64 v86, v246, v229, s[14:15]
	s_waitcnt lgkmcnt(3)
	v_add_f32_e32 v230, v82, v230
	v_cndmask_b32_e64 v88, v246, v230, s[18:19]
	s_waitcnt lgkmcnt(2)
	v_add_f32_e32 v231, v83, v231
	v_cndmask_b32_e64 v87, v246, v231, s[20:21]
	s_waitcnt lgkmcnt(1)
	v_add_f32_e32 v232, v84, v232
	v_cndmask_b32_e64 v138, v246, v232, s[22:23]
	s_waitcnt lgkmcnt(0)
	v_add_f32_e32 v233, v85, v233
	v_cndmask_b32_e64 v89, v246, v233, s[0:1]
	ds_read_b32 v208, v130 offset:1672
	ds_read_b32 v209, v131 offset:1672
	ds_read_b32 v210, v201 offset:1672
	ds_read_b32 v211, v203 offset:1672
	ds_read_b32 v212, v204 offset:1672
	ds_read_b32 v213, v205 offset:1672
	ds_read_b32 v214, v206 offset:1672
	ds_read_b32 v215, v207 offset:1672
	ds_read_b32 v216, v130 offset:1796
	ds_read_b32 v217, v131 offset:1796
	ds_read_b32 v228, v201 offset:1796
	ds_read_b32 v229, v203 offset:1796
	ds_read_b32 v230, v204 offset:1796
	ds_read_b32 v231, v205 offset:1796
	ds_read_b32 v232, v206 offset:1796
	ds_read_b32 v233, v207 offset:1796
	s_waitcnt lgkmcnt(15)
	v_add_f32_e32 v208, v78, v208
	v_cndmask_b32_e64 v137, v246, v208, s[36:37]
	s_waitcnt lgkmcnt(14)
	v_add_f32_e32 v209, v79, v209
	v_cndmask_b32_e64 v136, v246, v209, s[46:47]
	s_waitcnt lgkmcnt(13)
	v_add_f32_e32 v210, v80, v210
	v_cndmask_b32_e64 v141, v246, v210, s[10:11]
	s_waitcnt lgkmcnt(12)
	v_add_f32_e32 v211, v81, v211
	v_cndmask_b32_e64 v139, v246, v211, s[14:15]
	s_waitcnt lgkmcnt(11)
	v_add_f32_e32 v212, v74, v212
	v_cndmask_b32_e64 v195, v246, v212, s[18:19]
	s_waitcnt lgkmcnt(10)
	v_add_f32_e32 v213, v75, v213
	v_cndmask_b32_e64 v140, v246, v213, s[20:21]
	s_waitcnt lgkmcnt(9)
	v_add_f32_e32 v214, v76, v214
	v_cndmask_b32_e64 v199, v246, v214, s[22:23]
	s_waitcnt lgkmcnt(8)
	v_add_f32_e32 v215, v77, v215
	v_cndmask_b32_e64 v197, v246, v215, s[0:1]
	s_waitcnt lgkmcnt(7)
	v_add_f32_e32 v216, v70, v216
	v_cndmask_b32_e64 v198, v246, v216, s[36:37]
	s_waitcnt lgkmcnt(6)
	v_add_f32_e32 v217, v71, v217
	v_cndmask_b32_e64 v196, v246, v217, s[46:47]
	s_waitcnt lgkmcnt(5)
	v_add_f32_e32 v228, v72, v228
	v_cndmask_b32_e64 v202, v246, v228, s[10:11]
	s_waitcnt lgkmcnt(4)
	v_add_f32_e32 v229, v73, v229
	v_cndmask_b32_e64 v200, v246, v229, s[14:15]
	s_waitcnt lgkmcnt(3)
	v_add_f32_e32 v230, v66, v230
	v_cndmask_b32_e64 v203, v246, v230, s[18:19]
	s_waitcnt lgkmcnt(2)
	v_add_f32_e32 v231, v67, v231
	v_cndmask_b32_e64 v201, v246, v231, s[20:21]
	s_waitcnt lgkmcnt(1)
	v_add_f32_e32 v232, v68, v232
	v_cndmask_b32_e64 v205, v246, v232, s[22:23]
	s_waitcnt lgkmcnt(0)
	v_add_f32_e32 v233, v69, v233
	v_cndmask_b32_e64 v204, v246, v233, s[0:1]
	s_mov_b64 s[34:35], exec
	s_branch .LBB9_673
